# v098 + XCD-local rounds: non-leaders poll the XCC arrival counter for this round's target instead of the leader's generation bump (one hop less on release); generation waits made lag-proof (wait while
# baseline (speedup 1.0000x reference)
; __device__ __forceinline__ unsigned xb_ld(unsigned* p)              { return __hip_atomic_load(p, __ATOMIC_RELAXED, __HIP_MEMORY_SCOPE_AGENT); }
; __device__ __forceinline__ unsigned xb_add(unsigned* p, unsigned v) { return __hip_atomic_fetch_add(p, v, __ATOMIC_RELAXED, __HIP_MEMORY_SCOPE_AGENT); }
; #define XB_SPIN(cond, bar) do { unsigned _sp = 0; while (cond) { __builtin_amdgcn_s_sleep(1); \
;     if ((++_sp & 255u) == 0u) { if (xb_ld(&(bar)[XB_TMO])) break; if (_sp > XB_SPIN_CAP) { atomicAdd(&(bar)[XB_TMO], 1u); break; } } } } while (0)
; __device__ __forceinline__ void xcd_barrier(const XcdBarrier& b, int tid_in) {
;     ...
;     if (tid_in == 0) {
;         unsigned* bar = b.bar;
;         __builtin_amdgcn_s_waitcnt(0);
;         unsigned nloc = b.st[0], nx = b.st[1];
;         if (nloc == 0u) { xcd_barrier_complete(bar, b.x, nloc, nx); b.st[0] = nloc; b.st[1] = nx; }
;         const unsigned old = xb_add(&bar[XB_XSUB(b.x)], 1u);
;         const unsigned gen = old / nloc;
;         if (old + 1u == (gen + 1u) * nloc) {
;             __builtin_amdgcn_fence(__ATOMIC_RELEASE, "agent");
;             asm volatile("s_waitcnt vmcnt(0)" ::: "memory");
;             const unsigned og = xb_add(&bar[XB_TOP], 1u);
;             const unsigned tg = og / nx;
;             if (og + 1u == (tg + 1u) * nx) xb_add(&bar[XB_TOPGEN], 1u);
;             else XB_SPIN(xb_ld(&bar[XB_TOPGEN]) == tg, bar);
;             __builtin_amdgcn_fence(__ATOMIC_ACQUIRE, "agent");
;             xb_add(&bar[XB_XGEN(b.x)], 1u);
;             asm volatile("s_waitcnt vmcnt(0)" ::: "memory");
;         } else {
;             XB_SPIN(xb_ld(&bar[XB_XGEN(b.x)]) == gen, bar);
;             __builtin_amdgcn_fence(__ATOMIC_ACQUIRE, "agent");
;             asm volatile("s_waitcnt vmcnt(0)" ::: "memory");
;         }
.Lxb_s2done:
	v_mov_b32_e32 v16, 0
	s_nop 0
	global_load_dword v18, v16, s[0:1] offset:64 sc1
	v_readlane_b32 s4, v253, 41
	s_add_u32 s26, s0, s4
	s_addc_u32 s25, s1, 0
	v_mov_b32_e32 v1, s26
	v_add_co_u32_e32 v4, vcc, 0x1000, v1
	v_mov_b32_e32 v1, s25
	s_nop 0
	v_addc_co_u32_e32 v5, vcc, 0, v1, vcc
	flat_atomic_add v3, v[4:5], v221 offset:1024 sc0
	v_cvt_f32_u32_e32 v1, v2
	v_sub_u32_e32 v4, 0, v2
	v_rcp_iflag_f32_e32 v1, v1
	s_nop 0
	v_mul_f32_e32 v1, 0x4f7ffffe, v1
	v_cvt_u32_f32_e32 v1, v1
	v_mul_lo_u32 v4, v4, v1
	v_mul_hi_u32 v4, v1, v4
	v_add_u32_e32 v1, v1, v4
	s_waitcnt vmcnt(0) lgkmcnt(0)
	v_mul_hi_u32 v1, v3, v1
	v_mul_lo_u32 v4, v1, v2
	v_sub_u32_e32 v4, v3, v4
	v_cmp_ge_u32_e32 vcc, v4, v2
	v_add_u32_e32 v5, 1, v1
	s_nop 0
	v_cndmask_b32_e32 v1, v1, v5, vcc
	v_sub_u32_e32 v5, v4, v2
	v_cndmask_b32_e32 v4, v4, v5, vcc
	v_cmp_ge_u32_e32 vcc, v4, v2
	v_add_u32_e32 v4, 1, v1
	s_nop 0
	v_cndmask_b32_e32 v1, v1, v4, vcc
	v_add_u32_e32 v4, 1, v3
	v_mad_u64_u32 v[2:3], s[4:5], v2, v1, v[2:3]
	v_cmp_ne_u32_e32 vcc, v4, v2
	s_and_saveexec_b64 s[4:5], vcc
	s_xor_b64 s[4:5], exec, s[4:5]
	s_cbranch_execz .LBB0_552
	buffer_inv sc1
	s_add_i32 s6, s70, -2
	s_cmp_lt_u32 s6, 15
	s_cbranch_scc0 .Lxb_slow
	s_lshr_b32 s7, 0x6fff, s6
	s_and_b32 s7, s7, 1
	s_cbranch_scc0 .Lxb_slow
	v_readfirstlane_b32 s7, v18
	s_cmp_eq_u32 s7, 0
	s_cbranch_scc0 .Lxb_slow
	v_readfirstlane_b32 s7, v2
	s_add_u32 s8, s26, 0x1400
	s_addc_u32 s9, s25, 0
	s_mov_b32 s10, 0
.Lxb_fast:
	v_mov_b64_e32 v[2:3], s[8:9]
	flat_load_dword v0, v[2:3] sc1
	s_waitcnt vmcnt(0) lgkmcnt(0)
	v_readfirstlane_b32 s6, v0
	s_sub_i32 s6, s6, s7
	s_cmp_ge_i32 s6, 0
	s_cbranch_scc1 .LBB0_552
	s_add_i32 s10, s10, 1
	s_cmp_lt_u32 s10, 0x40000
	s_cbranch_scc0 .LBB0_552
	s_sleep 1
	s_branch .Lxb_fast
.Lxb_slow:
	v_mov_b32_e32 v0, s26
	v_add_co_u32_e32 v2, vcc, 0x2000, v0
	v_mov_b32_e32 v0, s25
	s_nop 0
	v_addc_co_u32_e32 v3, vcc, 0, v0, vcc
	flat_load_dword v0, v[2:3] offset:1024 sc1
	s_add_u32 s8, s26, 0x2400
	s_addc_u32 s9, s25, 0
	s_waitcnt vmcnt(0) lgkmcnt(0)
	v_cmp_ge_u32_e32 vcc, v1, v0
	s_and_saveexec_b64 s[6:7], vcc
	s_cbranch_execz .LBB0_551
	s_mov_b32 s27, 1
	s_mov_b64 s[10:11], 0
	s_branch .LBB0_535

; __device__ __forceinline__ unsigned xb_ld(unsigned* p)              { return __hip_atomic_load(p, __ATOMIC_RELAXED, __HIP_MEMORY_SCOPE_AGENT); }
; #define XB_SPIN(cond, bar) do { unsigned _sp = 0; while (cond) { __builtin_amdgcn_s_sleep(1); \
;     if ((++_sp & 255u) == 0u) { if (xb_ld(&(bar)[XB_TMO])) break; if (_sp > XB_SPIN_CAP) { atomicAdd(&(bar)[XB_TMO], 1u); break; } } } } while (0)
; __device__ __forceinline__ void xcd_barrier(const XcdBarrier& b, int tid_in) {
;     ...
;             XB_SPIN(xb_ld(&bar[XB_XGEN(b.x)]) == gen, bar);
;             __builtin_amdgcn_fence(__ATOMIC_ACQUIRE, "agent");
;             asm volatile("s_waitcnt vmcnt(0)" ::: "memory");
.LBB0_539:
	s_andn2_b64 s[14:15], s[14:15], exec
	s_and_b64 s[20:21], s[20:21], exec
	s_or_b64 s[14:15], s[14:15], s[20:21]
	s_and_saveexec_b64 s[20:21], s[18:19]
	s_cbranch_execz .LBB0_534
	v_mov_b64_e32 v[2:3], s[8:9]
	flat_load_dword v0, v[2:3] sc1
	s_add_i32 s27, s27, 1
	s_or_b64 s[14:15], s[14:15], exec
	s_waitcnt vmcnt(0) lgkmcnt(0)
	v_cmp_lt_u32_e32 vcc, v1, v0
	s_orn2_b64 s[16:17], vcc, exec
	s_branch .LBB0_534
